# v25: norm loops use permlane/DPP wave sums; FFN2 norm loop loads hoisted
# baseline (speedup 1.0000x reference)
; __device__ __forceinline__ unsigned pk_bf16(float lo, float hi) { f32x2 v; v.x = lo; v.y = hi; const bf16x2_t b = __builtin_convertvector(v, bf16x2_t); return __builtin_bit_cast(unsigned, b); }
; __device__ __forceinline__ void phase_norm(const Frame& F, const float* xl, const float* xc, const f16* x16, int l, int which, int r0, int nrows, int ci, int nc) {
;     ...
;     for (int row = gw; row < nrows; row += nw_) {
;         const bool lat = row < TL; const int mi = lat ? (row >> 12) : 8;
;         const float* sh = F.MOD + ((size_t)l * 9 + mi) * NMOD + (3 * which) * DM; const float* sc = sh + DM;
;         float v[2][8]; float ss = 0.f;
;         if (x16) {
;             const f16* xp = x16 + (size_t)row * DM;
; #pragma unroll
;             for (int j = 0; j < 2; ++j) { const f16x8 t = *(const f16x8*)(xp + j * 512 + F.lane * 8);
; #pragma unroll
;                 for (int e = 0; e < 8; ++e) v[j][e] = (float)t[e]; }
;         } else {
;             const float* xp = lat ? xl + (size_t)row * DM : xc + (size_t)(row - TL) * DM;
; #pragma unroll
;             for (int j = 0; j < 2; ++j) { const f32x4 a = *(const f32x4*)(xp + j * 512 + F.lane * 8), b = *(const f32x4*)(xp + j * 512 + F.lane * 8 + 4);
; #pragma unroll
;                 for (int e = 0; e < 4; ++e) { v[j][e] = a[e]; v[j][4 + e] = b[e]; } }
;         }
; #pragma unroll
;         for (int j = 0; j < 2; ++j)
; #pragma unroll
;             for (int e = 0; e < 8; ++e) ss += v[j][e] * v[j][e];
;         ss = wave_sum(ss);
;         const float rstd = rsqrtf(ss * (1.0f / DM) + 1e-6f);
; #pragma unroll
;         for (int j = 0; j < 2; ++j) { const int k = j * 512 + F.lane * 8;
;             float o[8];
; #pragma unroll
;             for (int q = 0; q < 2; ++q) { const f32x4 w = *(const f32x4*)(nw + k + 4 * q), s1 = *(const f32x4*)(sc + k + 4 * q), s0 = *(const f32x4*)(sh + k + 4 * q);
; #pragma unroll
;                 for (int e = 0; e < 4; ++e) o[4 * q + e] = v[j][4 * q + e] * rstd * w[e] * (1.0f + s1[e]) + s0[e]; }
;             u32x4 pk;
;             if (true) { pk.x = pk_bf16(o[0], o[1]); pk.y = pk_bf16(o[2], o[3]); pk.z = pk_bf16(o[4], o[5]); pk.w = pk_bf16(o[6], o[7]); }
;             else { pk.x = pk_f16(o[0], o[1]); pk.y = pk_f16(o[2], o[3]); pk.z = pk_f16(o[4], o[5]); pk.w = pk_f16(o[6], o[7]); }
;             *(u32x4*)(F.H16 + (size_t)row * DM + k) = pk; }
.LBB0_94:
	s_min_i32 s0, s8, 0x8000
	s_ashr_i32 s0, s0, 12
	s_ashr_i32 s1, s0, 31
	s_mul_i32 s2, s90, 9
	s_add_u32 s0, s2, s0
	s_addc_u32 s1, s14, s1
	s_mul_i32 s1, s1, 0x9000
	s_mul_hi_u32 s2, s0, 0x9000
	s_add_i32 s2, s2, s1
	s_mul_i32 s0, s0, 0x9000
	s_add_u32 s28, s6, s0
	s_addc_u32 s29, s7, s2
	s_add_u32 s30, s28, 0x1000
	s_addc_u32 s31, s29, 0
	v_lshlrev_b32_e32 v31, 2, v18
	global_load_dwordx4 v[32:35], v[20:21], off offset:16
	global_load_dwordx4 v[36:39], v[20:21], off
	global_load_dwordx4 v[40:43], v31, s[30:31] offset:16
	global_load_dwordx4 v[44:47], v31, s[30:31]
	global_load_dwordx4 v[48:51], v31, s[28:29] offset:16
	global_load_dwordx4 v[52:55], v31, s[28:29]
	s_waitcnt vmcnt(9)
	v_pk_mul_f32 v[56:57], v[10:11], v[10:11]
	v_pk_mul_f32 v[58:59], v[12:13], v[12:13]
	v_add_f32_e32 v56, v57, v56
	v_add_f32_e32 v56, v58, v56
	s_waitcnt vmcnt(8)
	v_pk_mul_f32 v[60:61], v[14:15], v[14:15]
	v_add_f32_e32 v56, v59, v56
	v_add_f32_e32 v56, v60, v56
	v_pk_mul_f32 v[62:63], v[16:17], v[16:17]
	v_add_f32_e32 v56, v61, v56
	v_add_f32_e32 v56, v62, v56
	s_waitcnt vmcnt(7)
	v_pk_mul_f32 v[64:65], v[2:3], v[2:3]
	v_add_f32_e32 v56, v63, v56
	v_add_f32_e32 v56, v64, v56
	v_pk_mul_f32 v[66:67], v[4:5], v[4:5]
	v_add_f32_e32 v56, v65, v56
	v_add_f32_e32 v56, v66, v56
	s_waitcnt vmcnt(6)
	v_pk_mul_f32 v[68:69], v[6:7], v[6:7]
	v_add_f32_e32 v56, v67, v56
	v_add_f32_e32 v56, v68, v56
	v_pk_mul_f32 v[70:71], v[8:9], v[8:9]
	v_add_f32_e32 v56, v69, v56
	v_add_f32_e32 v56, v70, v56
	v_add_f32_e32 v56, v71, v56
	s_waitcnt lgkmcnt(0)
	v_mov_b32_e32 v57, v56
	s_nop 1
	v_permlane32_swap_b32_e32 v56, v57
	v_add_f32_e32 v56, v56, v57
	v_mov_b32_e32 v57, v56
	s_nop 1
	v_permlane16_swap_b32_e32 v56, v57
	v_add_f32_e32 v56, v56, v57
	s_nop 1
	v_add_f32_dpp v56, v56, v56 row_ror:8 row_mask:0xf bank_mask:0xf
	s_nop 1
	v_add_f32_dpp v56, v56, v56 row_ror:4 row_mask:0xf bank_mask:0xf
	s_nop 1
	v_add_f32_dpp v56, v56, v56 row_ror:2 row_mask:0xf bank_mask:0xf
	s_nop 1
	v_add_f32_dpp v56, v56, v56 row_ror:1 row_mask:0xf bank_mask:0xf
	s_add_u32 s8, s8, s10
	s_addc_u32 s9, s9, s11
	s_add_u32 s18, s18, s20
	s_addc_u32 s19, s19, s21
	s_add_u32 s22, s22, s24
	s_addc_u32 s23, s23, s25
	s_cmp_lt_i32 s8, 0x8800
	v_fmamk_f32 v56, v56, 0x3a800000, v235
	v_mul_f32_e32 v57, 0x4b800000, v56
	v_cmp_gt_f32_e32 vcc, s88, v56
	s_nop 1
	v_cndmask_b32_e32 v56, v56, v57, vcc
	v_rsq_f32_e32 v58, v56
	v_lshl_add_u64 v[56:57], v[22:23], 0, s[26:27]
	v_mul_f32_e32 v59, 0x45800000, v58
	v_cndmask_b32_e32 v58, v58, v59, vcc
	v_pk_mul_f32 v[10:11], v[10:11], v[58:59] op_sel_hi:[1,0]
	v_pk_mul_f32 v[12:13], v[12:13], v[58:59] op_sel_hi:[1,0]
	v_pk_mul_f32 v[14:15], v[14:15], v[58:59] op_sel_hi:[1,0]
	v_pk_mul_f32 v[16:17], v[16:17], v[58:59] op_sel_hi:[1,0]
	v_pk_mul_f32 v[2:3], v[2:3], v[58:59] op_sel_hi:[1,0]
	s_waitcnt vmcnt(5)
	v_pk_mul_f32 v[14:15], v[32:33], v[14:15]
	s_waitcnt vmcnt(4)
	v_pk_mul_f32 v[10:11], v[36:37], v[10:11]
	v_pk_mul_f32 v[12:13], v[38:39], v[12:13]
	v_pk_mul_f32 v[16:17], v[34:35], v[16:17]
	s_waitcnt vmcnt(2)
	v_pk_add_f32 v[32:33], v[44:45], 1.0 op_sel_hi:[1,0]
	v_pk_add_f32 v[34:35], v[46:47], 1.0 op_sel_hi:[1,0]
	v_pk_add_f32 v[36:37], v[40:41], 1.0 op_sel_hi:[1,0]
	v_pk_add_f32 v[38:39], v[42:43], 1.0 op_sel_hi:[1,0]
	s_waitcnt vmcnt(0)
	v_pk_fma_f32 v[10:11], v[32:33], v[10:11], v[52:53]
	v_pk_fma_f32 v[12:13], v[34:35], v[12:13], v[54:55]
	v_pk_fma_f32 v[14:15], v[36:37], v[14:15], v[48:49]
	v_pk_fma_f32 v[16:17], v[38:39], v[16:17], v[50:51]
	v_cvt_pk_bf16_f32 v10, v10, v11
	v_cvt_pk_bf16_f32 v11, v12, v13
	v_cvt_pk_bf16_f32 v12, v14, v15
	v_cvt_pk_bf16_f32 v13, v16, v17
	global_store_dwordx4 v[56:57], v[10:13], off
	global_load_dwordx4 v[10:13], v[20:21], off offset:2048
	s_nop 0
	global_load_dwordx4 v[14:17], v0, s[30:31]
	global_load_dwordx4 v[32:35], v[20:21], off offset:2064
	global_load_dwordx4 v[36:39], v0, s[30:31] offset:16
	global_load_dwordx4 v[40:43], v31, s[28:29] offset:2048
	global_load_dwordx4 v[44:47], v31, s[28:29] offset:2064
	v_pk_mul_f32 v[4:5], v[4:5], v[58:59] op_sel_hi:[1,0]
	v_pk_mul_f32 v[6:7], v[6:7], v[58:59] op_sel_hi:[1,0]
	v_pk_mul_f32 v[8:9], v[8:9], v[58:59] op_sel_hi:[1,0]
	s_waitcnt vmcnt(5)
	v_pk_mul_f32 v[2:3], v[10:11], v[2:3]
	s_waitcnt vmcnt(4)
	v_pk_add_f32 v[10:11], v[14:15], 1.0 op_sel_hi:[1,0]
	v_pk_mul_f32 v[4:5], v[12:13], v[4:5]
	v_pk_add_f32 v[12:13], v[16:17], 1.0 op_sel_hi:[1,0]
	s_waitcnt vmcnt(3)
	v_pk_mul_f32 v[6:7], v[32:33], v[6:7]
	s_waitcnt vmcnt(2)
	v_pk_add_f32 v[14:15], v[36:37], 1.0 op_sel_hi:[1,0]
	v_pk_mul_f32 v[8:9], v[34:35], v[8:9]
	v_pk_add_f32 v[16:17], v[38:39], 1.0 op_sel_hi:[1,0]
	s_waitcnt vmcnt(1)
	v_pk_fma_f32 v[2:3], v[10:11], v[2:3], v[40:41]
	v_pk_fma_f32 v[4:5], v[12:13], v[4:5], v[42:43]
	s_waitcnt vmcnt(0)
	v_pk_fma_f32 v[6:7], v[14:15], v[6:7], v[44:45]
	v_pk_fma_f32 v[8:9], v[16:17], v[8:9], v[46:47]
	v_cvt_pk_bf16_f32 v2, v2, v3
	v_cvt_pk_bf16_f32 v3, v4, v5
	v_cvt_pk_bf16_f32 v4, v6, v7
	v_cvt_pk_bf16_f32 v5, v8, v9
	global_store_dwordx4 v[56:57], v[2:5], off offset:1024
	s_cbranch_scc0 .LBB0_100

; __device__ __forceinline__ unsigned pk_bf16(float lo, float hi) { f32x2 v; v.x = lo; v.y = hi; const bf16x2_t b = __builtin_convertvector(v, bf16x2_t); return __builtin_bit_cast(unsigned, b); }
; __device__ __forceinline__ void phase_norm(const Frame& F, const float* xl, const float* xc, const f16* x16, int l, int which, int r0, int nrows, int ci, int nc) {
;     ...
;     for (int row = gw; row < nrows; row += nw_) {
;         const bool lat = row < TL; const int mi = lat ? (row >> 12) : 8;
;         const float* sh = F.MOD + ((size_t)l * 9 + mi) * NMOD + (3 * which) * DM; const float* sc = sh + DM;
;         float v[2][8]; float ss = 0.f;
;         if (x16) {
;             const f16* xp = x16 + (size_t)row * DM;
; #pragma unroll
;             for (int j = 0; j < 2; ++j) { const f16x8 t = *(const f16x8*)(xp + j * 512 + F.lane * 8);
; #pragma unroll
;                 for (int e = 0; e < 8; ++e) v[j][e] = (float)t[e]; }
;         } else {
;             const float* xp = lat ? xl + (size_t)row * DM : xc + (size_t)(row - TL) * DM;
; #pragma unroll
;             for (int j = 0; j < 2; ++j) { const f32x4 a = *(const f32x4*)(xp + j * 512 + F.lane * 8), b = *(const f32x4*)(xp + j * 512 + F.lane * 8 + 4);
; #pragma unroll
;                 for (int e = 0; e < 4; ++e) { v[j][e] = a[e]; v[j][4 + e] = b[e]; } }
;         }
; #pragma unroll
;         for (int j = 0; j < 2; ++j)
; #pragma unroll
;             for (int e = 0; e < 8; ++e) ss += v[j][e] * v[j][e];
;         ss = wave_sum(ss);
;         const float rstd = rsqrtf(ss * (1.0f / DM) + 1e-6f);
; #pragma unroll
;         for (int j = 0; j < 2; ++j) { const int k = j * 512 + F.lane * 8;
;             float o[8];
; #pragma unroll
;             for (int q = 0; q < 2; ++q) { const f32x4 w = *(const f32x4*)(nw + k + 4 * q), s1 = *(const f32x4*)(sc + k + 4 * q), s0 = *(const f32x4*)(sh + k + 4 * q);
; #pragma unroll
;                 for (int e = 0; e < 4; ++e) o[4 * q + e] = v[j][4 * q + e] * rstd * w[e] * (1.0f + s1[e]) + s0[e]; }
;             u32x4 pk;
;             if (true) { pk.x = pk_bf16(o[0], o[1]); pk.y = pk_bf16(o[2], o[3]); pk.z = pk_bf16(o[4], o[5]); pk.w = pk_bf16(o[6], o[7]); }
;             else { pk.x = pk_f16(o[0], o[1]); pk.y = pk_f16(o[2], o[3]); pk.z = pk_f16(o[4], o[5]); pk.w = pk_f16(o[6], o[7]); }
;             *(u32x4*)(F.H16 + (size_t)row * DM + k) = pk; }
.LBB0_407:
	v_add_co_u32_e32 v16, vcc, s3, v6
	s_ashr_i32 s0, s4, 12
	s_nop 0
	v_addc_co_u32_e32 v17, vcc, -1, v7, vcc
	global_load_dwordx4 v[16:19], v[16:17], off
	v_add_co_u32_e32 v20, vcc, s5, v6
	s_ashr_i32 s1, s0, 31
	s_nop 0
	v_addc_co_u32_e32 v21, vcc, -1, v7, vcc
	global_load_dwordx4 v[20:23], v[20:21], off offset:-3072
	s_add_u32 s0, s12, s0
	s_addc_u32 s1, s7, s1
	s_mul_hi_u32 s2, s0, 0x9000
	s_mul_i32 s1, s1, 0x9000
	s_mul_i32 s0, s0, 0x9000
	s_add_i32 s2, s2, s1
	s_add_u32 s0, s18, s0
	s_addc_u32 s1, s19, s2
	s_add_u32 s10, s0, 0x3000
	s_addc_u32 s11, s1, 0
	s_add_u32 s16, s0, 0x4000
	s_addc_u32 s17, s1, 0
	global_load_dwordx4 v[24:27], v0, s[16:17] offset:16
	global_load_dwordx4 v[28:31], v[2:3], off offset:16
	global_load_dwordx4 v[32:35], v[2:3], off
	global_load_dwordx4 v[36:39], v0, s[10:11] offset:16
	global_load_dwordx4 v[40:43], v0, s[10:11]
	global_load_dwordx4 v[44:47], v0, s[16:17]
	s_add_i32 s4, s4, s6
	s_cmpk_gt_i32 s4, 0x7fff
	s_waitcnt vmcnt(7)
	v_cvt_f32_f16_e32 v52, v16
	v_cvt_f32_f16_sdwa v53, v16 dst_sel:DWORD dst_unused:UNUSED_PAD src0_sel:WORD_1
	v_cvt_f32_f16_e32 v48, v19
	v_cvt_f32_f16_sdwa v49, v19 dst_sel:DWORD dst_unused:UNUSED_PAD src0_sel:WORD_1
	v_cvt_f32_f16_e32 v50, v18
	v_cvt_f32_f16_sdwa v51, v18 dst_sel:DWORD dst_unused:UNUSED_PAD src0_sel:WORD_1
	v_cvt_f32_f16_e32 v18, v17
	v_cvt_f32_f16_sdwa v19, v17 dst_sel:DWORD dst_unused:UNUSED_PAD src0_sel:WORD_1
	v_pk_mul_f32 v[62:63], v[52:53], v[52:53]
	s_waitcnt vmcnt(6)
	v_cvt_f32_f16_e32 v54, v23
	v_cvt_f32_f16_sdwa v55, v23 dst_sel:DWORD dst_unused:UNUSED_PAD src0_sel:WORD_1
	v_cvt_f32_f16_e32 v56, v22
	v_cvt_f32_f16_sdwa v57, v22 dst_sel:DWORD dst_unused:UNUSED_PAD src0_sel:WORD_1
	v_pk_mul_f32 v[22:23], v[18:19], v[18:19]
	v_add_f32_e32 v15, v62, v63
	v_add_f32_e32 v15, v22, v15
	v_cvt_f32_f16_e32 v58, v21
	v_cvt_f32_f16_sdwa v59, v21 dst_sel:DWORD dst_unused:UNUSED_PAD src0_sel:WORD_1
	v_cvt_f32_f16_e32 v60, v20
	v_cvt_f32_f16_sdwa v61, v20 dst_sel:DWORD dst_unused:UNUSED_PAD src0_sel:WORD_1
	v_pk_mul_f32 v[20:21], v[50:51], v[50:51]
	v_add_f32_e32 v15, v23, v15
	v_add_f32_e32 v15, v20, v15
	v_pk_mul_f32 v[16:17], v[48:49], v[48:49]
	v_add_f32_e32 v15, v21, v15
	v_add_f32_e32 v15, v16, v15
	v_pk_mul_f32 v[70:71], v[60:61], v[60:61]
	v_add_f32_e32 v15, v17, v15
	v_add_f32_e32 v15, v70, v15
	v_pk_mul_f32 v[68:69], v[58:59], v[58:59]
	v_add_f32_e32 v15, v71, v15
	v_add_f32_e32 v15, v68, v15
	v_pk_mul_f32 v[66:67], v[56:57], v[56:57]
	v_add_f32_e32 v15, v69, v15
	v_add_f32_e32 v15, v66, v15
	v_pk_mul_f32 v[64:65], v[54:55], v[54:55]
	v_add_f32_e32 v15, v67, v15
	v_add_f32_e32 v15, v64, v15
	v_add_f32_e32 v15, v65, v15
	s_waitcnt lgkmcnt(0)
	v_mov_b32_e32 v16, v15
	s_nop 1
	v_permlane32_swap_b32_e32 v15, v16
	v_add_f32_e32 v15, v15, v16
	v_mov_b32_e32 v16, v15
	s_nop 1
	v_permlane16_swap_b32_e32 v15, v16
	v_add_f32_e32 v15, v15, v16
	s_nop 1
	v_add_f32_dpp v15, v15, v15 row_ror:8 row_mask:0xf bank_mask:0xf
	s_nop 1
	v_add_f32_dpp v15, v15, v15 row_ror:4 row_mask:0xf bank_mask:0xf
	s_nop 1
	v_add_f32_dpp v15, v15, v15 row_ror:2 row_mask:0xf bank_mask:0xf
	s_nop 1
	v_add_f32_dpp v15, v15, v15 row_ror:1 row_mask:0xf bank_mask:0xf
	s_waitcnt vmcnt(0)
	v_pk_add_f32 v[22:23], v[44:45], 1.0 op_sel_hi:[1,0]
	v_pk_add_f32 v[16:17], v[24:25], 1.0 op_sel_hi:[1,0]
	v_pk_add_f32 v[24:25], v[26:27], 1.0 op_sel_hi:[1,0]
	v_fmamk_f32 v15, v15, 0x3a800000, v235
	v_mul_f32_e32 v20, 0x4b800000, v15
	v_cmp_gt_f32_e32 vcc, s88, v15
	s_nop 1
	v_cndmask_b32_e32 v15, v15, v20, vcc
	v_rsq_f32_e32 v15, v15
	v_pk_add_f32 v[20:21], v[46:47], 1.0 op_sel_hi:[1,0]
	v_mul_f32_e32 v26, 0x45800000, v15
	v_cndmask_b32_e32 v44, v15, v26, vcc
	v_pk_mul_f32 v[26:27], v[44:45], v[52:53] op_sel_hi:[0,1]
	v_pk_mul_f32 v[18:19], v[44:45], v[18:19] op_sel_hi:[0,1]
	v_pk_mul_f32 v[46:47], v[44:45], v[50:51] op_sel_hi:[0,1]
	v_pk_mul_f32 v[48:49], v[44:45], v[48:49] op_sel_hi:[0,1]
	v_pk_mul_f32 v[26:27], v[32:33], v[26:27]
	v_pk_mul_f32 v[18:19], v[34:35], v[18:19]
	v_pk_mul_f32 v[28:29], v[28:29], v[46:47]
	v_pk_mul_f32 v[30:31], v[30:31], v[48:49]
	v_pk_fma_f32 v[22:23], v[22:23], v[26:27], v[40:41]
	v_pk_fma_f32 v[18:19], v[20:21], v[18:19], v[42:43]
	v_pk_fma_f32 v[20:21], v[16:17], v[28:29], v[36:37]
	v_pk_fma_f32 v[24:25], v[24:25], v[30:31], v[38:39]
	v_cvt_pk_bf16_f32 v16, v22, v23
	v_cvt_pk_bf16_f32 v17, v18, v19
	v_cvt_pk_bf16_f32 v18, v20, v21
	v_cvt_pk_bf16_f32 v19, v24, v25
	global_store_dwordx4 v[6:7], v[16:19], off
	global_load_dwordx4 v[16:19], v[4:5], off
	s_nop 0
	global_load_dwordx4 v[20:23], v14, s[16:17]
	global_load_dwordx4 v[24:27], v[4:5], off offset:16
	global_load_dwordx4 v[28:31], v14, s[16:17] offset:16
	global_load_dwordx4 v[32:35], v14, s[10:11]
	global_load_dwordx4 v[36:39], v14, s[10:11] offset:16
	v_pk_mul_f32 v[40:41], v[44:45], v[60:61] op_sel_hi:[0,1]
	v_pk_mul_f32 v[42:43], v[44:45], v[58:59] op_sel_hi:[0,1]
	v_pk_mul_f32 v[46:47], v[44:45], v[56:57] op_sel_hi:[0,1]
	v_pk_mul_f32 v[44:45], v[44:45], v[54:55] op_sel_hi:[0,1]
	s_waitcnt vmcnt(5)
	v_pk_mul_f32 v[16:17], v[16:17], v[40:41]
	s_waitcnt vmcnt(4)
	v_pk_add_f32 v[20:21], v[20:21], 1.0 op_sel_hi:[1,0]
	v_pk_mul_f32 v[18:19], v[18:19], v[42:43]
	v_pk_add_f32 v[22:23], v[22:23], 1.0 op_sel_hi:[1,0]
	s_waitcnt vmcnt(3)
	v_pk_mul_f32 v[24:25], v[24:25], v[46:47]
	s_waitcnt vmcnt(2)
	v_pk_add_f32 v[28:29], v[28:29], 1.0 op_sel_hi:[1,0]
	v_pk_mul_f32 v[26:27], v[26:27], v[44:45]
	v_pk_add_f32 v[30:31], v[30:31], 1.0 op_sel_hi:[1,0]
	s_waitcnt vmcnt(1)
	v_pk_fma_f32 v[16:17], v[20:21], v[16:17], v[32:33]
	v_pk_fma_f32 v[18:19], v[22:23], v[18:19], v[34:35]
	s_waitcnt vmcnt(0)
	v_pk_fma_f32 v[20:21], v[28:29], v[24:25], v[36:37]
	v_pk_fma_f32 v[22:23], v[30:31], v[26:27], v[38:39]
	v_cvt_pk_bf16_f32 v16, v16, v17
	v_cvt_pk_bf16_f32 v17, v18, v19
	v_cvt_pk_bf16_f32 v18, v20, v21
	v_cvt_pk_bf16_f32 v19, v22, v23
	global_store_dwordx4 v[6:7], v[16:19], off offset:1024
	v_lshl_add_u64 v[6:7], v[6:7], 0, s[8:9]
	s_cbranch_scc0 .LBB0_407

; __device__ __forceinline__ unsigned pk_bf16(float lo, float hi) { f32x2 v; v.x = lo; v.y = hi; const bf16x2_t b = __builtin_convertvector(v, bf16x2_t); return __builtin_bit_cast(unsigned, b); }
; __device__ __forceinline__ void phase_norm(const Frame& F, const float* xl, const float* xc, const f16* x16, int l, int which, int r0, int nrows, int ci, int nc) {
;     ...
;     for (int row = gw; row < nrows; row += nw_) {
;         const bool lat = row < TL; const int mi = lat ? (row >> 12) : 8;
;         const float* sh = F.MOD + ((size_t)l * 9 + mi) * NMOD + (3 * which) * DM; const float* sc = sh + DM;
;         float v[2][8]; float ss = 0.f;
;         if (x16) {
;             const f16* xp = x16 + (size_t)row * DM;
; #pragma unroll
;             for (int j = 0; j < 2; ++j) { const f16x8 t = *(const f16x8*)(xp + j * 512 + F.lane * 8);
; #pragma unroll
;                 for (int e = 0; e < 8; ++e) v[j][e] = (float)t[e]; }
;         } else {
;             const float* xp = lat ? xl + (size_t)row * DM : xc + (size_t)(row - TL) * DM;
; #pragma unroll
;             for (int j = 0; j < 2; ++j) { const f32x4 a = *(const f32x4*)(xp + j * 512 + F.lane * 8), b = *(const f32x4*)(xp + j * 512 + F.lane * 8 + 4);
; #pragma unroll
;                 for (int e = 0; e < 4; ++e) { v[j][e] = a[e]; v[j][4 + e] = b[e]; } }
;         }
; #pragma unroll
;         for (int j = 0; j < 2; ++j)
; #pragma unroll
;             for (int e = 0; e < 8; ++e) ss += v[j][e] * v[j][e];
;         ss = wave_sum(ss);
;         const float rstd = rsqrtf(ss * (1.0f / DM) + 1e-6f);
; #pragma unroll
;         for (int j = 0; j < 2; ++j) { const int k = j * 512 + F.lane * 8;
;             float o[8];
; #pragma unroll
;             for (int q = 0; q < 2; ++q) { const f32x4 w = *(const f32x4*)(nw + k + 4 * q), s1 = *(const f32x4*)(sc + k + 4 * q), s0 = *(const f32x4*)(sh + k + 4 * q);
; #pragma unroll
;                 for (int e = 0; e < 4; ++e) o[4 * q + e] = v[j][4 * q + e] * rstd * w[e] * (1.0f + s1[e]) + s0[e]; }
;             u32x4 pk;
;             if (true) { pk.x = pk_bf16(o[0], o[1]); pk.y = pk_bf16(o[2], o[3]); pk.z = pk_bf16(o[4], o[5]); pk.w = pk_bf16(o[6], o[7]); }
;             else { pk.x = pk_f16(o[0], o[1]); pk.y = pk_f16(o[2], o[3]); pk.z = pk_f16(o[4], o[5]); pk.w = pk_f16(o[6], o[7]); }
;             *(u32x4*)(F.H16 + (size_t)row * DM + k) = pk; }
.LBB0_458:
	v_add_co_u32_e32 v18, vcc, s14, v6
	s_min_i32 s1, s4, 0x8000
	s_nop 0
	v_addc_co_u32_e32 v19, vcc, -1, v7, vcc
	global_load_dwordx4 v[18:21], v[18:19], off
	v_add_co_u32_e32 v22, vcc, s12, v6
	s_ashr_i32 s1, s1, 12
	s_nop 0
	v_addc_co_u32_e32 v23, vcc, -1, v7, vcc
	global_load_dwordx4 v[22:25], v[22:23], off offset:-3072
	s_ashr_i32 s2, s1, 31
	s_add_u32 s1, s13, s1
	s_addc_u32 s2, s5, s2
	s_mul_hi_u32 s3, s1, 0x9000
	s_mul_i32 s2, s2, 0x9000
	s_mul_i32 s1, s1, 0x9000
	s_add_i32 s3, s3, s2
	s_add_u32 s1, s6, s1
	s_addc_u32 s2, s7, s3
	s_add_u32 s8, s1, 0x3000
	s_addc_u32 s9, s2, 0
	s_add_u32 s10, s1, 0x4000
	s_addc_u32 s11, s2, 0
	global_load_dwordx4 v[26:29], v0, s[10:11] offset:16
	global_load_dwordx4 v[30:33], v[2:3], off offset:16
	global_load_dwordx4 v[34:37], v[2:3], off
	global_load_dwordx4 v[38:41], v0, s[8:9] offset:16
	global_load_dwordx4 v[42:45], v0, s[8:9]
	global_load_dwordx4 v[46:49], v0, s[10:11]
	s_add_i32 s4, s4, s0
	s_cmp_lt_i32 s4, 0x8800
	s_waitcnt vmcnt(7)
	v_cvt_f32_f16_e32 v54, v18
	v_cvt_f32_f16_sdwa v55, v18 dst_sel:DWORD dst_unused:UNUSED_PAD src0_sel:WORD_1
	v_cvt_f32_f16_e32 v50, v21
	v_cvt_f32_f16_sdwa v51, v21 dst_sel:DWORD dst_unused:UNUSED_PAD src0_sel:WORD_1
	v_cvt_f32_f16_e32 v52, v20
	v_cvt_f32_f16_sdwa v53, v20 dst_sel:DWORD dst_unused:UNUSED_PAD src0_sel:WORD_1
	v_cvt_f32_f16_e32 v20, v19
	v_cvt_f32_f16_sdwa v21, v19 dst_sel:DWORD dst_unused:UNUSED_PAD src0_sel:WORD_1
	v_pk_mul_f32 v[64:65], v[54:55], v[54:55]
	s_waitcnt vmcnt(6)
	v_cvt_f32_f16_e32 v56, v25
	v_cvt_f32_f16_sdwa v57, v25 dst_sel:DWORD dst_unused:UNUSED_PAD src0_sel:WORD_1
	v_cvt_f32_f16_e32 v58, v24
	v_cvt_f32_f16_sdwa v59, v24 dst_sel:DWORD dst_unused:UNUSED_PAD src0_sel:WORD_1
	v_pk_mul_f32 v[24:25], v[20:21], v[20:21]
	v_add_f32_e32 v17, v64, v65
	v_add_f32_e32 v17, v24, v17
	v_cvt_f32_f16_e32 v60, v23
	v_cvt_f32_f16_sdwa v61, v23 dst_sel:DWORD dst_unused:UNUSED_PAD src0_sel:WORD_1
	v_cvt_f32_f16_e32 v62, v22
	v_cvt_f32_f16_sdwa v63, v22 dst_sel:DWORD dst_unused:UNUSED_PAD src0_sel:WORD_1
	v_pk_mul_f32 v[22:23], v[52:53], v[52:53]
	v_add_f32_e32 v17, v25, v17
	v_add_f32_e32 v17, v22, v17
	v_pk_mul_f32 v[18:19], v[50:51], v[50:51]
	v_add_f32_e32 v17, v23, v17
	v_add_f32_e32 v17, v18, v17
	v_pk_mul_f32 v[72:73], v[62:63], v[62:63]
	v_add_f32_e32 v17, v19, v17
	v_add_f32_e32 v17, v72, v17
	v_pk_mul_f32 v[70:71], v[60:61], v[60:61]
	v_add_f32_e32 v17, v73, v17
	v_add_f32_e32 v17, v70, v17
	v_pk_mul_f32 v[68:69], v[58:59], v[58:59]
	v_add_f32_e32 v17, v71, v17
	v_add_f32_e32 v17, v68, v17
	v_pk_mul_f32 v[66:67], v[56:57], v[56:57]
	v_add_f32_e32 v17, v69, v17
	v_add_f32_e32 v17, v66, v17
	v_add_f32_e32 v17, v67, v17
	s_waitcnt lgkmcnt(0)
	v_mov_b32_e32 v18, v17
	s_nop 1
	v_permlane32_swap_b32_e32 v17, v18
	v_add_f32_e32 v17, v17, v18
	v_mov_b32_e32 v18, v17
	s_nop 1
	v_permlane16_swap_b32_e32 v17, v18
	v_add_f32_e32 v17, v17, v18
	s_nop 1
	v_add_f32_dpp v17, v17, v17 row_ror:8 row_mask:0xf bank_mask:0xf
	s_nop 1
	v_add_f32_dpp v17, v17, v17 row_ror:4 row_mask:0xf bank_mask:0xf
	s_nop 1
	v_add_f32_dpp v17, v17, v17 row_ror:2 row_mask:0xf bank_mask:0xf
	s_nop 1
	v_add_f32_dpp v17, v17, v17 row_ror:1 row_mask:0xf bank_mask:0xf
	s_waitcnt vmcnt(0)
	v_pk_add_f32 v[24:25], v[46:47], 1.0 op_sel_hi:[1,0]
	v_pk_add_f32 v[18:19], v[26:27], 1.0 op_sel_hi:[1,0]
	v_pk_add_f32 v[26:27], v[28:29], 1.0 op_sel_hi:[1,0]
	v_fmamk_f32 v17, v17, 0x3a800000, v235
	v_mul_f32_e32 v22, 0x4b800000, v17
	v_cmp_gt_f32_e32 vcc, s88, v17
	s_nop 1
	v_cndmask_b32_e32 v17, v17, v22, vcc
	v_rsq_f32_e32 v17, v17
	v_pk_add_f32 v[22:23], v[48:49], 1.0 op_sel_hi:[1,0]
	v_mul_f32_e32 v28, 0x45800000, v17
	v_cndmask_b32_e32 v46, v17, v28, vcc
	v_pk_mul_f32 v[28:29], v[46:47], v[54:55] op_sel_hi:[0,1]
	v_pk_mul_f32 v[20:21], v[46:47], v[20:21] op_sel_hi:[0,1]
	v_pk_mul_f32 v[48:49], v[46:47], v[52:53] op_sel_hi:[0,1]
	v_pk_mul_f32 v[50:51], v[46:47], v[50:51] op_sel_hi:[0,1]
	v_pk_mul_f32 v[28:29], v[34:35], v[28:29]
	v_pk_mul_f32 v[20:21], v[36:37], v[20:21]
	v_pk_mul_f32 v[30:31], v[30:31], v[48:49]
	v_pk_mul_f32 v[32:33], v[32:33], v[50:51]
	v_pk_fma_f32 v[24:25], v[24:25], v[28:29], v[42:43]
	v_pk_fma_f32 v[20:21], v[22:23], v[20:21], v[44:45]
	v_pk_fma_f32 v[22:23], v[18:19], v[30:31], v[38:39]
	v_pk_fma_f32 v[26:27], v[26:27], v[32:33], v[40:41]
	v_cvt_pk_bf16_f32 v18, v24, v25
	v_cvt_pk_bf16_f32 v19, v20, v21
	v_cvt_pk_bf16_f32 v20, v22, v23
	v_cvt_pk_bf16_f32 v21, v26, v27
	global_store_dwordx4 v[6:7], v[18:21], off
	global_load_dwordx4 v[18:21], v[4:5], off
	s_nop 0
	global_load_dwordx4 v[22:25], v16, s[10:11]
	global_load_dwordx4 v[26:29], v[4:5], off offset:16
	global_load_dwordx4 v[30:33], v16, s[10:11] offset:16
	global_load_dwordx4 v[34:37], v16, s[8:9]
	global_load_dwordx4 v[38:41], v16, s[8:9] offset:16
	v_pk_mul_f32 v[42:43], v[46:47], v[62:63] op_sel_hi:[0,1]
	v_pk_mul_f32 v[44:45], v[46:47], v[60:61] op_sel_hi:[0,1]
	v_pk_mul_f32 v[48:49], v[46:47], v[58:59] op_sel_hi:[0,1]
	v_pk_mul_f32 v[46:47], v[46:47], v[56:57] op_sel_hi:[0,1]
	s_waitcnt vmcnt(5)
	v_pk_mul_f32 v[18:19], v[18:19], v[42:43]
	s_waitcnt vmcnt(4)
	v_pk_add_f32 v[22:23], v[22:23], 1.0 op_sel_hi:[1,0]
	v_pk_mul_f32 v[20:21], v[20:21], v[44:45]
	v_pk_add_f32 v[24:25], v[24:25], 1.0 op_sel_hi:[1,0]
	s_waitcnt vmcnt(3)
	v_pk_mul_f32 v[26:27], v[26:27], v[48:49]
	s_waitcnt vmcnt(2)
	v_pk_add_f32 v[30:31], v[30:31], 1.0 op_sel_hi:[1,0]
	v_pk_mul_f32 v[28:29], v[28:29], v[46:47]
	v_pk_add_f32 v[32:33], v[32:33], 1.0 op_sel_hi:[1,0]
	s_waitcnt vmcnt(1)
	v_pk_fma_f32 v[18:19], v[22:23], v[18:19], v[34:35]
	v_pk_fma_f32 v[20:21], v[24:25], v[20:21], v[36:37]
	s_waitcnt vmcnt(0)
	v_pk_fma_f32 v[22:23], v[30:31], v[26:27], v[38:39]
	v_pk_fma_f32 v[24:25], v[32:33], v[28:29], v[40:41]
	v_cvt_pk_bf16_f32 v18, v18, v19
	v_cvt_pk_bf16_f32 v19, v20, v21
	v_cvt_pk_bf16_f32 v20, v22, v23
	v_cvt_pk_bf16_f32 v21, v24, v25
	global_store_dwordx4 v[6:7], v[18:21], off offset:1024
	v_lshl_add_u64 v[6:7], v[6:7], 0, v[8:9]
	s_cbranch_scc1 .LBB0_458

; __device__ __forceinline__ unsigned pk_bf16(float lo, float hi) { f32x2 v; v.x = lo; v.y = hi; const bf16x2_t b = __builtin_convertvector(v, bf16x2_t); return __builtin_bit_cast(unsigned, b); }
; __device__ __forceinline__ void phase_norm(const Frame& F, const float* xl, const float* xc, const f16* x16, int l, int which, int r0, int nrows, int ci, int nc) {
;     ...
;     for (int row = gw; row < nrows; row += nw_) {
;         const bool lat = row < TL; const int mi = lat ? (row >> 12) : 8;
;         const float* sh = F.MOD + ((size_t)l * 9 + mi) * NMOD + (3 * which) * DM; const float* sc = sh + DM;
;         float v[2][8]; float ss = 0.f;
;         if (x16) {
;             const f16* xp = x16 + (size_t)row * DM;
; #pragma unroll
;             for (int j = 0; j < 2; ++j) { const f16x8 t = *(const f16x8*)(xp + j * 512 + F.lane * 8);
; #pragma unroll
;                 for (int e = 0; e < 8; ++e) v[j][e] = (float)t[e]; }
;         } else {
;             const float* xp = lat ? xl + (size_t)row * DM : xc + (size_t)(row - TL) * DM;
; #pragma unroll
;             for (int j = 0; j < 2; ++j) { const f32x4 a = *(const f32x4*)(xp + j * 512 + F.lane * 8), b = *(const f32x4*)(xp + j * 512 + F.lane * 8 + 4);
; #pragma unroll
;                 for (int e = 0; e < 4; ++e) { v[j][e] = a[e]; v[j][4 + e] = b[e]; } }
;         }
; #pragma unroll
;         for (int j = 0; j < 2; ++j)
; #pragma unroll
;             for (int e = 0; e < 8; ++e) ss += v[j][e] * v[j][e];
;         ss = wave_sum(ss);
;         const float rstd = rsqrtf(ss * (1.0f / DM) + 1e-6f);
; #pragma unroll
;         for (int j = 0; j < 2; ++j) { const int k = j * 512 + F.lane * 8;
;             float o[8];
; #pragma unroll
;             for (int q = 0; q < 2; ++q) { const f32x4 w = *(const f32x4*)(nw + k + 4 * q), s1 = *(const f32x4*)(sc + k + 4 * q), s0 = *(const f32x4*)(sh + k + 4 * q);
; #pragma unroll
;                 for (int e = 0; e < 4; ++e) o[4 * q + e] = v[j][4 * q + e] * rstd * w[e] * (1.0f + s1[e]) + s0[e]; }
;             u32x4 pk;
;             if (true) { pk.x = pk_bf16(o[0], o[1]); pk.y = pk_bf16(o[2], o[3]); pk.z = pk_bf16(o[4], o[5]); pk.w = pk_bf16(o[6], o[7]); }
;             else { pk.x = pk_f16(o[0], o[1]); pk.y = pk_f16(o[2], o[3]); pk.z = pk_f16(o[4], o[5]); pk.w = pk_f16(o[6], o[7]); }
;             *(u32x4*)(F.H16 + (size_t)row * DM + k) = pk; }
.LBB0_960:
	v_add_co_u32_e32 v18, vcc, s20, v6
	s_min_i32 s3, s0, 0x8000
	s_nop 0
	v_addc_co_u32_e32 v19, vcc, -1, v7, vcc
	global_load_dwordx4 v[18:21], v[18:19], off
	v_add_co_u32_e32 v22, vcc, s17, v6
	s_ashr_i32 s3, s3, 12
	s_nop 0
	v_addc_co_u32_e32 v23, vcc, -1, v7, vcc
	global_load_dwordx4 v[22:25], v[22:23], off offset:-3072
	s_ashr_i32 s6, s3, 31
	s_add_u32 s3, s22, s3
	s_addc_u32 s6, s14, s6
	s_mul_hi_u32 s7, s3, 0x9000
	s_mul_i32 s6, s6, 0x9000
	s_mul_i32 s3, s3, 0x9000
	s_add_i32 s7, s7, s6
	s_add_u32 s3, s4, s3
	s_addc_u32 s9, s5, s7
	s_add_u32 s6, s3, 0x6000
	s_addc_u32 s7, s9, 0
	s_add_u32 s8, s3, 0x7000
	s_addc_u32 s9, s9, 0
	global_load_dwordx4 v[26:29], v0, s[8:9] offset:16
	global_load_dwordx4 v[30:33], v[2:3], off offset:16
	global_load_dwordx4 v[34:37], v[2:3], off
	global_load_dwordx4 v[38:41], v0, s[6:7] offset:16
	global_load_dwordx4 v[42:45], v0, s[6:7]
	global_load_dwordx4 v[46:49], v0, s[8:9]
	global_load_dwordx4 v[100:103], v[4:5], off
	global_load_dwordx4 v[104:107], v16, s[8:9]
	global_load_dwordx4 v[108:111], v[4:5], off offset:16
	global_load_dwordx4 v[112:115], v16, s[8:9] offset:16
	global_load_dwordx4 v[116:119], v16, s[6:7]
	global_load_dwordx4 v[120:123], v16, s[6:7] offset:16
	s_add_i32 s0, s0, s2
	s_cmp_lt_i32 s0, s1
	s_waitcnt vmcnt(13)
	v_cvt_f32_f16_e32 v54, v18
	v_cvt_f32_f16_sdwa v55, v18 dst_sel:DWORD dst_unused:UNUSED_PAD src0_sel:WORD_1
	v_cvt_f32_f16_e32 v50, v21
	v_cvt_f32_f16_sdwa v51, v21 dst_sel:DWORD dst_unused:UNUSED_PAD src0_sel:WORD_1
	v_cvt_f32_f16_e32 v52, v20
	v_cvt_f32_f16_sdwa v53, v20 dst_sel:DWORD dst_unused:UNUSED_PAD src0_sel:WORD_1
	v_cvt_f32_f16_e32 v20, v19
	v_cvt_f32_f16_sdwa v21, v19 dst_sel:DWORD dst_unused:UNUSED_PAD src0_sel:WORD_1
	v_pk_mul_f32 v[64:65], v[54:55], v[54:55]
	s_waitcnt vmcnt(12)
	v_cvt_f32_f16_e32 v56, v25
	v_cvt_f32_f16_sdwa v57, v25 dst_sel:DWORD dst_unused:UNUSED_PAD src0_sel:WORD_1
	v_cvt_f32_f16_e32 v58, v24
	v_cvt_f32_f16_sdwa v59, v24 dst_sel:DWORD dst_unused:UNUSED_PAD src0_sel:WORD_1
	v_pk_mul_f32 v[24:25], v[20:21], v[20:21]
	v_add_f32_e32 v17, v64, v65
	v_add_f32_e32 v17, v24, v17
	v_cvt_f32_f16_e32 v60, v23
	v_cvt_f32_f16_sdwa v61, v23 dst_sel:DWORD dst_unused:UNUSED_PAD src0_sel:WORD_1
	v_cvt_f32_f16_e32 v62, v22
	v_cvt_f32_f16_sdwa v63, v22 dst_sel:DWORD dst_unused:UNUSED_PAD src0_sel:WORD_1
	v_pk_mul_f32 v[22:23], v[52:53], v[52:53]
	v_add_f32_e32 v17, v25, v17
	v_add_f32_e32 v17, v22, v17
	v_pk_mul_f32 v[18:19], v[50:51], v[50:51]
	v_add_f32_e32 v17, v23, v17
	v_add_f32_e32 v17, v18, v17
	v_pk_mul_f32 v[72:73], v[62:63], v[62:63]
	v_add_f32_e32 v17, v19, v17
	v_add_f32_e32 v17, v72, v17
	v_pk_mul_f32 v[70:71], v[60:61], v[60:61]
	v_add_f32_e32 v17, v73, v17
	v_add_f32_e32 v17, v70, v17
	v_pk_mul_f32 v[68:69], v[58:59], v[58:59]
	v_add_f32_e32 v17, v71, v17
	v_add_f32_e32 v17, v68, v17
	v_pk_mul_f32 v[66:67], v[56:57], v[56:57]
	v_add_f32_e32 v17, v69, v17
	v_add_f32_e32 v17, v66, v17
	v_add_f32_e32 v17, v67, v17
	v_mov_b32_e32 v18, v17
	s_nop 1
	v_permlane32_swap_b32_e32 v17, v18
	v_add_f32_e32 v17, v17, v18
	v_mov_b32_e32 v18, v17
	s_nop 1
	v_permlane16_swap_b32_e32 v17, v18
	v_add_f32_e32 v17, v17, v18
	s_nop 1
	v_add_f32_dpp v17, v17, v17 row_ror:8 row_mask:0xf bank_mask:0xf
	s_nop 1
	v_add_f32_dpp v17, v17, v17 row_ror:4 row_mask:0xf bank_mask:0xf
	s_nop 1
	v_add_f32_dpp v17, v17, v17 row_ror:2 row_mask:0xf bank_mask:0xf
	s_nop 1
	v_add_f32_dpp v17, v17, v17 row_ror:1 row_mask:0xf bank_mask:0xf
	s_waitcnt vmcnt(6)
	v_pk_add_f32 v[24:25], v[46:47], 1.0 op_sel_hi:[1,0]
	v_pk_add_f32 v[18:19], v[26:27], 1.0 op_sel_hi:[1,0]
	v_pk_add_f32 v[26:27], v[28:29], 1.0 op_sel_hi:[1,0]
	v_fmamk_f32 v17, v17, 0x3a800000, v235
	v_mul_f32_e32 v22, 0x4b800000, v17
	v_cmp_gt_f32_e32 vcc, s88, v17
	s_nop 1
	v_cndmask_b32_e32 v17, v17, v22, vcc
	v_rsq_f32_e32 v17, v17
	v_pk_add_f32 v[22:23], v[48:49], 1.0 op_sel_hi:[1,0]
	v_mul_f32_e32 v28, 0x45800000, v17
	v_cndmask_b32_e32 v46, v17, v28, vcc
	v_pk_mul_f32 v[28:29], v[46:47], v[54:55] op_sel_hi:[0,1]
	v_pk_mul_f32 v[20:21], v[46:47], v[20:21] op_sel_hi:[0,1]
	v_pk_mul_f32 v[48:49], v[46:47], v[52:53] op_sel_hi:[0,1]
	v_pk_mul_f32 v[50:51], v[46:47], v[50:51] op_sel_hi:[0,1]
	v_pk_mul_f32 v[28:29], v[34:35], v[28:29]
	v_pk_mul_f32 v[20:21], v[36:37], v[20:21]
	v_pk_mul_f32 v[30:31], v[30:31], v[48:49]
	v_pk_mul_f32 v[32:33], v[32:33], v[50:51]
	v_pk_fma_f32 v[24:25], v[24:25], v[28:29], v[42:43]
	v_pk_fma_f32 v[20:21], v[22:23], v[20:21], v[44:45]
	v_pk_fma_f32 v[22:23], v[18:19], v[30:31], v[38:39]
	v_pk_fma_f32 v[26:27], v[26:27], v[32:33], v[40:41]
	v_cvt_pk_bf16_f32 v18, v24, v25
	v_cvt_pk_bf16_f32 v19, v20, v21
	v_cvt_pk_bf16_f32 v20, v22, v23
	v_cvt_pk_bf16_f32 v21, v26, v27
	global_store_dwordx4 v[6:7], v[18:21], off
	v_pk_mul_f32 v[42:43], v[46:47], v[62:63] op_sel_hi:[0,1]
	v_pk_mul_f32 v[44:45], v[46:47], v[60:61] op_sel_hi:[0,1]
	v_pk_mul_f32 v[48:49], v[46:47], v[58:59] op_sel_hi:[0,1]
	v_pk_mul_f32 v[46:47], v[46:47], v[56:57] op_sel_hi:[0,1]
	s_waitcnt vmcnt(1)
	v_pk_mul_f32 v[100:101], v[100:101], v[42:43]
	v_pk_add_f32 v[104:105], v[104:105], 1.0 op_sel_hi:[1,0]
	v_pk_mul_f32 v[102:103], v[102:103], v[44:45]
	v_pk_add_f32 v[106:107], v[106:107], 1.0 op_sel_hi:[1,0]
	v_pk_mul_f32 v[108:109], v[108:109], v[48:49]
	v_pk_add_f32 v[112:113], v[112:113], 1.0 op_sel_hi:[1,0]
	v_pk_mul_f32 v[110:111], v[110:111], v[46:47]
	v_pk_add_f32 v[114:115], v[114:115], 1.0 op_sel_hi:[1,0]
	v_pk_fma_f32 v[100:101], v[104:105], v[100:101], v[116:117]
	v_pk_fma_f32 v[102:103], v[106:107], v[102:103], v[118:119]
	v_pk_fma_f32 v[104:105], v[112:113], v[108:109], v[120:121]
	v_pk_fma_f32 v[106:107], v[114:115], v[110:111], v[122:123]
	v_cvt_pk_bf16_f32 v100, v100, v101
	v_cvt_pk_bf16_f32 v101, v102, v103
	v_cvt_pk_bf16_f32 v102, v104, v105
	v_cvt_pk_bf16_f32 v103, v106, v107
	global_store_dwordx4 v[6:7], v[100:103], off offset:1024
	v_lshl_add_u64 v[6:7], v[6:7], 0, v[8:9]
	s_cbranch_scc1 .LBB0_960

; __device__ __forceinline__ unsigned pk_bf16(float lo, float hi) { f32x2 v; v.x = lo; v.y = hi; const bf16x2_t b = __builtin_convertvector(v, bf16x2_t); return __builtin_bit_cast(unsigned, b); }
; __device__ __forceinline__ void phase_norm(const Frame& F, const float* xl, const float* xc, const f16* x16, int l, int which, int r0, int nrows, int ci, int nc) {
;     ...
;     for (int row = gw; row < nrows; row += nw_) {
;         const bool lat = row < TL; const int mi = lat ? (row >> 12) : 8;
;         const float* sh = F.MOD + ((size_t)l * 9 + mi) * NMOD + (3 * which) * DM; const float* sc = sh + DM;
;         float v[2][8]; float ss = 0.f;
;         if (x16) {
;             const f16* xp = x16 + (size_t)row * DM;
; #pragma unroll
;             for (int j = 0; j < 2; ++j) { const f16x8 t = *(const f16x8*)(xp + j * 512 + F.lane * 8);
; #pragma unroll
;                 for (int e = 0; e < 8; ++e) v[j][e] = (float)t[e]; }
;         } else {
;             const float* xp = lat ? xl + (size_t)row * DM : xc + (size_t)(row - TL) * DM;
; #pragma unroll
;             for (int j = 0; j < 2; ++j) { const f32x4 a = *(const f32x4*)(xp + j * 512 + F.lane * 8), b = *(const f32x4*)(xp + j * 512 + F.lane * 8 + 4);
; #pragma unroll
;                 for (int e = 0; e < 4; ++e) { v[j][e] = a[e]; v[j][4 + e] = b[e]; } }
;         }
; #pragma unroll
;         for (int j = 0; j < 2; ++j)
; #pragma unroll
;             for (int e = 0; e < 8; ++e) ss += v[j][e] * v[j][e];
;         ss = wave_sum(ss);
;         const float rstd = rsqrtf(ss * (1.0f / DM) + 1e-6f);
; #pragma unroll
;         for (int j = 0; j < 2; ++j) { const int k = j * 512 + F.lane * 8;
;             float o[8];
; #pragma unroll
;             for (int q = 0; q < 2; ++q) { const f32x4 w = *(const f32x4*)(nw + k + 4 * q), s1 = *(const f32x4*)(sc + k + 4 * q), s0 = *(const f32x4*)(sh + k + 4 * q);
; #pragma unroll
;                 for (int e = 0; e < 4; ++e) o[4 * q + e] = v[j][4 * q + e] * rstd * w[e] * (1.0f + s1[e]) + s0[e]; }
;             u32x4 pk;
;             if (true) { pk.x = pk_bf16(o[0], o[1]); pk.y = pk_bf16(o[2], o[3]); pk.z = pk_bf16(o[4], o[5]); pk.w = pk_bf16(o[6], o[7]); }
;             else { pk.x = pk_f16(o[0], o[1]); pk.y = pk_f16(o[2], o[3]); pk.z = pk_f16(o[4], o[5]); pk.w = pk_f16(o[6], o[7]); }
;             *(u32x4*)(F.H16 + (size_t)row * DM + k) = pk; }
.LBB0_1200:
	v_add_co_u32_e32 v14, vcc, s20, v4
	s_ashr_i32 s2, s4, 12
	s_nop 0
	v_addc_co_u32_e32 v15, vcc, -1, v5, vcc
	global_load_dwordx4 v[14:17], v[14:15], off
	v_add_co_u32_e32 v18, vcc, s14, v4
	s_ashr_i32 s3, s2, 31
	s_nop 0
	v_addc_co_u32_e32 v19, vcc, -1, v5, vcc
	global_load_dwordx4 v[18:21], v[18:19], off offset:-3072
	s_add_u32 s2, s1, s2
	s_addc_u32 s3, s0, s3
	s_mul_hi_u32 s5, s2, 0x9000
	s_mul_i32 s3, s3, 0x9000
	s_mul_i32 s2, s2, 0x9000
	s_add_i32 s5, s5, s3
	s_add_u32 s16, s6, s2
	s_addc_u32 s17, s7, s5
	s_add_u32 s18, s16, 0x1000
	s_addc_u32 s19, s17, 0
	global_load_dwordx4 v[22:25], v0, s[18:19] offset:16
	global_load_dwordx4 v[26:29], v[2:3], off offset:16
	global_load_dwordx4 v[30:33], v[2:3], off
	global_load_dwordx4 v[34:37], v0, s[16:17] offset:16
	global_load_dwordx4 v[38:41], v0, s[16:17]
	global_load_dwordx4 v[42:45], v0, s[18:19]
	s_add_i32 s4, s4, s10
	s_cmp_lt_i32 s4, 0x8000
	s_waitcnt vmcnt(7)
	v_cvt_f32_f16_e32 v50, v14
	v_cvt_f32_f16_sdwa v51, v14 dst_sel:DWORD dst_unused:UNUSED_PAD src0_sel:WORD_1
	v_cvt_f32_f16_e32 v46, v17
	v_cvt_f32_f16_sdwa v47, v17 dst_sel:DWORD dst_unused:UNUSED_PAD src0_sel:WORD_1
	v_cvt_f32_f16_e32 v48, v16
	v_cvt_f32_f16_sdwa v49, v16 dst_sel:DWORD dst_unused:UNUSED_PAD src0_sel:WORD_1
	v_cvt_f32_f16_e32 v16, v15
	v_cvt_f32_f16_sdwa v17, v15 dst_sel:DWORD dst_unused:UNUSED_PAD src0_sel:WORD_1
	v_pk_mul_f32 v[60:61], v[50:51], v[50:51]
	s_waitcnt vmcnt(6)
	v_cvt_f32_f16_e32 v52, v21
	v_cvt_f32_f16_sdwa v53, v21 dst_sel:DWORD dst_unused:UNUSED_PAD src0_sel:WORD_1
	v_cvt_f32_f16_e32 v54, v20
	v_cvt_f32_f16_sdwa v55, v20 dst_sel:DWORD dst_unused:UNUSED_PAD src0_sel:WORD_1
	v_pk_mul_f32 v[20:21], v[16:17], v[16:17]
	v_add_f32_e32 v13, v60, v61
	v_add_f32_e32 v13, v20, v13
	v_cvt_f32_f16_e32 v56, v19
	v_cvt_f32_f16_sdwa v57, v19 dst_sel:DWORD dst_unused:UNUSED_PAD src0_sel:WORD_1
	v_cvt_f32_f16_e32 v58, v18
	v_cvt_f32_f16_sdwa v59, v18 dst_sel:DWORD dst_unused:UNUSED_PAD src0_sel:WORD_1
	v_pk_mul_f32 v[18:19], v[48:49], v[48:49]
	v_add_f32_e32 v13, v21, v13
	v_add_f32_e32 v13, v18, v13
	v_pk_mul_f32 v[14:15], v[46:47], v[46:47]
	v_add_f32_e32 v13, v19, v13
	v_add_f32_e32 v13, v14, v13
	v_pk_mul_f32 v[68:69], v[58:59], v[58:59]
	v_add_f32_e32 v13, v15, v13
	v_add_f32_e32 v13, v68, v13
	v_pk_mul_f32 v[66:67], v[56:57], v[56:57]
	v_add_f32_e32 v13, v69, v13
	v_add_f32_e32 v13, v66, v13
	v_pk_mul_f32 v[64:65], v[54:55], v[54:55]
	v_add_f32_e32 v13, v67, v13
	v_add_f32_e32 v13, v64, v13
	v_pk_mul_f32 v[62:63], v[52:53], v[52:53]
	v_add_f32_e32 v13, v65, v13
	v_add_f32_e32 v13, v62, v13
	v_add_f32_e32 v13, v63, v13
	s_waitcnt lgkmcnt(0)
	v_mov_b32_e32 v14, v13
	s_nop 1
	v_permlane32_swap_b32_e32 v13, v14
	v_add_f32_e32 v13, v13, v14
	v_mov_b32_e32 v14, v13
	s_nop 1
	v_permlane16_swap_b32_e32 v13, v14
	v_add_f32_e32 v13, v13, v14
	s_nop 1
	v_add_f32_dpp v13, v13, v13 row_ror:8 row_mask:0xf bank_mask:0xf
	s_nop 1
	v_add_f32_dpp v13, v13, v13 row_ror:4 row_mask:0xf bank_mask:0xf
	s_nop 1
	v_add_f32_dpp v13, v13, v13 row_ror:2 row_mask:0xf bank_mask:0xf
	s_nop 1
	v_add_f32_dpp v13, v13, v13 row_ror:1 row_mask:0xf bank_mask:0xf
	s_waitcnt vmcnt(0)
	v_pk_add_f32 v[20:21], v[42:43], 1.0 op_sel_hi:[1,0]
	v_pk_add_f32 v[14:15], v[22:23], 1.0 op_sel_hi:[1,0]
	v_pk_add_f32 v[22:23], v[24:25], 1.0 op_sel_hi:[1,0]
	v_fmamk_f32 v13, v13, 0x3a800000, v235
	v_mul_f32_e32 v18, 0x4b800000, v13
	v_cmp_gt_f32_e32 vcc, s88, v13
	s_nop 1
	v_cndmask_b32_e32 v13, v13, v18, vcc
	v_rsq_f32_e32 v13, v13
	v_pk_add_f32 v[18:19], v[44:45], 1.0 op_sel_hi:[1,0]
	v_mul_f32_e32 v24, 0x45800000, v13
	v_cndmask_b32_e32 v42, v13, v24, vcc
	v_pk_mul_f32 v[24:25], v[42:43], v[50:51] op_sel_hi:[0,1]
	v_pk_mul_f32 v[16:17], v[42:43], v[16:17] op_sel_hi:[0,1]
	v_pk_mul_f32 v[44:45], v[42:43], v[48:49] op_sel_hi:[0,1]
	v_pk_mul_f32 v[46:47], v[42:43], v[46:47] op_sel_hi:[0,1]
	v_pk_mul_f32 v[24:25], v[30:31], v[24:25]
	v_pk_mul_f32 v[16:17], v[32:33], v[16:17]
	v_pk_mul_f32 v[26:27], v[26:27], v[44:45]
	v_pk_mul_f32 v[28:29], v[28:29], v[46:47]
	v_pk_fma_f32 v[20:21], v[20:21], v[24:25], v[38:39]
	v_pk_fma_f32 v[16:17], v[18:19], v[16:17], v[40:41]
	v_pk_fma_f32 v[18:19], v[14:15], v[26:27], v[34:35]
	v_pk_fma_f32 v[22:23], v[22:23], v[28:29], v[36:37]
	v_cvt_pk_bf16_f32 v14, v20, v21
	v_cvt_pk_bf16_f32 v15, v16, v17
	v_cvt_pk_bf16_f32 v16, v18, v19
	v_cvt_pk_bf16_f32 v17, v22, v23
	global_store_dwordx4 v[4:5], v[14:17], off
	global_load_dwordx4 v[14:17], v[2:3], off offset:2048
	s_nop 0
	global_load_dwordx4 v[18:21], v12, s[18:19]
	global_load_dwordx4 v[22:25], v[2:3], off offset:2064
	global_load_dwordx4 v[26:29], v12, s[18:19] offset:16
	global_load_dwordx4 v[30:33], v0, s[16:17] offset:2048
	global_load_dwordx4 v[34:37], v0, s[16:17] offset:2064
	v_pk_mul_f32 v[38:39], v[42:43], v[58:59] op_sel_hi:[0,1]
	v_pk_mul_f32 v[40:41], v[42:43], v[56:57] op_sel_hi:[0,1]
	v_pk_mul_f32 v[44:45], v[42:43], v[54:55] op_sel_hi:[0,1]
	v_pk_mul_f32 v[42:43], v[42:43], v[52:53] op_sel_hi:[0,1]
	s_waitcnt vmcnt(5)
	v_pk_mul_f32 v[14:15], v[14:15], v[38:39]
	s_waitcnt vmcnt(4)
	v_pk_add_f32 v[18:19], v[18:19], 1.0 op_sel_hi:[1,0]
	v_pk_mul_f32 v[16:17], v[16:17], v[40:41]
	v_pk_add_f32 v[20:21], v[20:21], 1.0 op_sel_hi:[1,0]
	s_waitcnt vmcnt(3)
	v_pk_mul_f32 v[22:23], v[22:23], v[44:45]
	s_waitcnt vmcnt(2)
	v_pk_add_f32 v[26:27], v[26:27], 1.0 op_sel_hi:[1,0]
	v_pk_mul_f32 v[24:25], v[24:25], v[42:43]
	v_pk_add_f32 v[28:29], v[28:29], 1.0 op_sel_hi:[1,0]
	s_waitcnt vmcnt(1)
	v_pk_fma_f32 v[14:15], v[18:19], v[14:15], v[30:31]
	v_pk_fma_f32 v[16:17], v[20:21], v[16:17], v[32:33]
	s_waitcnt vmcnt(0)
	v_pk_fma_f32 v[18:19], v[26:27], v[22:23], v[34:35]
	v_pk_fma_f32 v[20:21], v[28:29], v[24:25], v[36:37]
	v_cvt_pk_bf16_f32 v14, v14, v15
	v_cvt_pk_bf16_f32 v15, v16, v17
	v_cvt_pk_bf16_f32 v16, v18, v19
	v_cvt_pk_bf16_f32 v17, v20, v21
	global_store_dwordx4 v[4:5], v[14:17], off offset:1024
	v_lshl_add_u64 v[4:5], v[4:5], 0, s[8:9]
	s_cbranch_scc1 .LBB0_1200
